# v29 + attention row-max tree rebuilt from 23 v_max/v_max3 to two interleaved v_max3_i32 chains (16 instructions, same integer max)
# baseline (speedup 1.0000x reference)
; DI float ex2(float x) { return __builtin_amdgcn_exp2f(x); }
; template <int MODE>
; DI void flash_pass(AState& st, const bf16x8* qf, u64 tmask, u64 wmask,
;                    const bf16_t* kbase, size_t kld, const bf16_t* kpe, const bf16_t* vtbase, const float* fbias,
;                    int tq, u64 mysel, bf16_t* smem) {
;     ...
;       int im = (int)0x80000000;
; #pragma unroll
;       for (int r = 0; r < 16; ++r) im = max(im, max(__float_as_int(s0[r]), __float_as_int(s1[r])));
;       im = max(im, __shfl_xor(im, 32));
;       constexpr int TBITS = 0x41800000;
;       f32x16 e0, e1;
; #pragma unroll
;       for (int r = 0; r < 16; ++r) { e0[r] = ex2(s0[r]); e1[r] = ex2(s1[r]); }
;       if (__any(im > TBITS)) {
;         const float d = im > TBITS ? __int_as_float(im) : 0.f;
;         const float a = ex2(-d);
; #pragma unroll
;         for (int r = 0; r < 16; ++r) { e0[r] = ex2(s0[r] - d); e1[r] = ex2(s1[r] - d); st.o[0][r] *= a; st.o[1][r] *= a; }
;         st.l *= a; st.m += d;
; #pragma unroll
;         for (int r = 0; r < 16; ++r) st.mr[r] = -st.m;
;       }
.LBB0_612:
	s_nop 10
	v_max3_i32 v2, v81, v65, v80
	v_max3_i32 v3, v64, v82, v66
	v_max3_i32 v2, v2, v83, v67
	v_max3_i32 v3, v3, v84, v68
	v_max3_i32 v2, v2, v85, v69
	v_max3_i32 v3, v3, v86, v70
	v_max3_i32 v2, v2, v87, v71
	v_max3_i32 v3, v3, v88, v72
	v_max3_i32 v2, v2, v89, v73
	v_max3_i32 v3, v3, v90, v74
	v_max3_i32 v2, v2, v91, v75
	v_max3_i32 v3, v3, v92, v76
	v_max3_i32 v2, v2, v93, v77
	v_max3_i32 v3, v3, v94, v78
	v_max3_i32 v2, v2, v95, v79
	v_max_i32_e32 v2, v2, v3
	v_mov_b32_e32 v3, v2
	s_nop 1
	v_permlane32_swap_b32_e32 v3, v2
	v_max_i32_e32 v2, v2, v3
	v_cmp_lt_i32_e32 vcc, s88, v2
	s_cbranch_vccz .LBB0_614
	s_nop 0
	v_cndmask_b32_e32 v49, 0, v2, vcc
	v_sub_f32_e32 v2, v80, v49
	v_exp_f32_e32 v151, v2
	v_sub_f32_e32 v2, v64, v49
	v_exp_f32_e32 v147, v2
	v_sub_f32_e32 v2, v81, v49
	v_exp_f32_e32 v152, v2
	v_sub_f32_e32 v2, v65, v49
	v_exp_f32_e32 v148, v2
	v_sub_f32_e32 v2, v82, v49
	v_exp_f32_e32 v153, v2
	v_sub_f32_e32 v2, v66, v49
	v_exp_f32_e32 v149, v2
	v_sub_f32_e32 v2, v83, v49
	v_exp_f32_e32 v154, v2
	v_sub_f32_e32 v2, v67, v49
	v_exp_f32_e32 v150, v2
	v_sub_f32_e32 v2, v84, v49
	v_exp_f32_e32 v80, v2
	v_sub_f32_e32 v2, v68, v49
	v_exp_f32_e32 v10, v2
	v_sub_f32_e32 v2, v85, v49
	v_exp_f32_e32 v81, v2
	v_sub_f32_e32 v2, v69, v49
	v_exp_f32_e32 v11, v2
	v_sub_f32_e32 v2, v86, v49
	v_exp_f32_e32 v82, v2
	v_sub_f32_e32 v2, v70, v49
	v_exp_f32_e32 v12, v2
	v_sub_f32_e32 v2, v87, v49
	v_exp_f32_e32 v83, v2
	v_sub_f32_e32 v2, v71, v49
	v_exp_f32_e64 v48, -v49
	v_exp_f32_e32 v13, v2
	v_sub_f32_e32 v2, v88, v49
	v_sub_f32_e32 v3, v89, v49
	v_sub_f32_e32 v4, v90, v49
	v_sub_f32_e32 v5, v91, v49
	v_sub_f32_e32 v6, v92, v49
	v_sub_f32_e32 v7, v93, v49
	v_sub_f32_e32 v8, v94, v49
	v_sub_f32_e32 v9, v95, v49
	v_exp_f32_e32 v14, v2
	v_sub_f32_e32 v2, v72, v49
	v_exp_f32_e32 v15, v3
	v_sub_f32_e32 v3, v73, v49
	v_exp_f32_e32 v64, v4
	v_sub_f32_e32 v4, v74, v49
	v_exp_f32_e32 v65, v5
	v_sub_f32_e32 v5, v75, v49
	v_exp_f32_e32 v66, v6
	v_sub_f32_e32 v6, v76, v49
	v_exp_f32_e32 v67, v7
	v_sub_f32_e32 v7, v77, v49
	v_exp_f32_e32 v68, v8
	v_sub_f32_e32 v8, v78, v49
	v_exp_f32_e32 v69, v9
	v_sub_f32_e32 v9, v79, v49
	v_exp_f32_e32 v2, v2
	v_exp_f32_e32 v3, v3
	v_exp_f32_e32 v4, v4
	v_exp_f32_e32 v5, v5
	v_exp_f32_e32 v6, v6
	v_exp_f32_e32 v7, v7
	v_exp_f32_e32 v8, v8
	v_exp_f32_e32 v9, v9
	v_add_f32_e32 v146, v146, v49
	v_pk_mul_f32 v[46:47], v[46:47], v[48:49] op_sel_hi:[1,0]
	v_pk_mul_f32 v[44:45], v[44:45], v[48:49] op_sel_hi:[1,0]
	v_pk_mul_f32 v[42:43], v[42:43], v[48:49] op_sel_hi:[1,0]
	v_pk_mul_f32 v[40:41], v[40:41], v[48:49] op_sel_hi:[1,0]
	v_pk_mul_f32 v[38:39], v[38:39], v[48:49] op_sel_hi:[1,0]
	v_pk_mul_f32 v[36:37], v[36:37], v[48:49] op_sel_hi:[1,0]
	v_pk_mul_f32 v[34:35], v[34:35], v[48:49] op_sel_hi:[1,0]
	v_pk_mul_f32 v[32:33], v[32:33], v[48:49] op_sel_hi:[1,0]
	v_pk_mul_f32 v[30:31], v[30:31], v[48:49] op_sel_hi:[1,0]
	v_pk_mul_f32 v[28:29], v[28:29], v[48:49] op_sel_hi:[1,0]
	v_pk_mul_f32 v[26:27], v[26:27], v[48:49] op_sel_hi:[1,0]
	v_pk_mul_f32 v[24:25], v[24:25], v[48:49] op_sel_hi:[1,0]
	v_pk_mul_f32 v[22:23], v[22:23], v[48:49] op_sel_hi:[1,0]
	v_pk_mul_f32 v[20:21], v[20:21], v[48:49] op_sel_hi:[1,0]
	v_pk_mul_f32 v[18:19], v[18:19], v[48:49] op_sel_hi:[1,0]
	v_pk_mul_f32 v[16:17], v[16:17], v[48:49] op_sel_hi:[1,0]
	v_mul_f32_e32 v178, v178, v48
	v_xor_b32_e32 v48, 0x80000000, v146
	v_mov_b32_e32 v49, v48
	v_mov_b32_e32 v50, v48
	v_mov_b32_e32 v51, v48
	v_mov_b32_e32 v52, v48
	v_mov_b32_e32 v53, v48
	v_mov_b32_e32 v54, v48
	v_mov_b32_e32 v55, v48
	v_mov_b32_e32 v56, v48
	v_mov_b32_e32 v57, v48
	v_mov_b32_e32 v58, v48
	v_mov_b32_e32 v59, v48
	v_mov_b32_e32 v60, v48
	v_mov_b32_e32 v61, v48
	v_mov_b32_e32 v62, v48
	v_mov_b32_e32 v63, v48
	s_branch .LBB0_615

; DI float ex2(float x) { return __builtin_amdgcn_exp2f(x); }
; template <int MODE>
; DI void flash_pass(AState& st, const bf16x8* qf, u64 tmask, u64 wmask,
;                    const bf16_t* kbase, size_t kld, const bf16_t* kpe, const bf16_t* vtbase, const float* fbias,
;                    int tq, u64 mysel, bf16_t* smem) {
;     ...
;       int im = (int)0x80000000;
; #pragma unroll
;       for (int r = 0; r < 16; ++r) im = max(im, max(__float_as_int(s0[r]), __float_as_int(s1[r])));
;       im = max(im, __shfl_xor(im, 32));
;       constexpr int TBITS = 0x41800000;
;       f32x16 e0, e1;
; #pragma unroll
;       for (int r = 0; r < 16; ++r) { e0[r] = ex2(s0[r]); e1[r] = ex2(s1[r]); }
.LBB0_622:
	s_nop 10
	v_max3_i32 v2, v81, v65, v80
	v_max3_i32 v3, v64, v82, v66
	v_max3_i32 v2, v2, v83, v67
	v_max3_i32 v3, v3, v84, v68
	v_max3_i32 v2, v2, v85, v69
	v_max3_i32 v3, v3, v86, v70
	v_max3_i32 v2, v2, v87, v71
	v_max3_i32 v3, v3, v88, v72
	v_max3_i32 v2, v2, v89, v73
	v_max3_i32 v3, v3, v90, v74
	v_max3_i32 v2, v2, v91, v75
	v_max3_i32 v3, v3, v92, v76
	v_max3_i32 v2, v2, v93, v77
	v_max3_i32 v3, v3, v94, v78
	v_max3_i32 v2, v2, v95, v79
	v_max_i32_e32 v2, v2, v3
	v_mov_b32_e32 v3, v2
	s_nop 1
	v_permlane32_swap_b32_e32 v3, v2
	v_max_i32_e32 v2, v2, v3
	v_cmp_lt_i32_e32 vcc, s88, v2
	s_cbranch_vccnz .LBB0_603
	v_exp_f32_e32 v151, v80
	v_exp_f32_e32 v147, v64
	v_exp_f32_e32 v152, v81
	v_exp_f32_e32 v148, v65
	v_exp_f32_e32 v153, v82
	v_exp_f32_e32 v149, v66
	v_exp_f32_e32 v154, v83
	v_exp_f32_e32 v150, v67
	v_exp_f32_e32 v80, v84
	v_exp_f32_e32 v10, v68
	v_exp_f32_e32 v81, v85
	v_exp_f32_e32 v11, v69
	v_exp_f32_e32 v82, v86
	v_exp_f32_e32 v12, v70
	v_exp_f32_e32 v83, v87
	v_exp_f32_e32 v13, v71
	v_exp_f32_e32 v14, v88
	v_exp_f32_e32 v2, v72
	v_exp_f32_e32 v15, v89
	v_exp_f32_e32 v3, v73
	v_exp_f32_e32 v64, v90
	v_exp_f32_e32 v4, v74
	v_exp_f32_e32 v65, v91
	v_exp_f32_e32 v5, v75
	v_exp_f32_e32 v66, v92
	v_exp_f32_e32 v6, v76
	v_exp_f32_e32 v67, v93
	v_exp_f32_e32 v7, v77
	v_exp_f32_e32 v68, v94
	v_exp_f32_e32 v8, v78
	v_exp_f32_e32 v69, v95
	v_exp_f32_e32 v9, v79
	s_branch .LBB0_604

; DI float ex2(float x) { return __builtin_amdgcn_exp2f(x); }
; template <int MODE>
; DI void flash_pass(AState& st, const bf16x8* qf, u64 tmask, u64 wmask,
;                    const bf16_t* kbase, size_t kld, const bf16_t* kpe, const bf16_t* vtbase, const float* fbias,
;                    int tq, u64 mysel, bf16_t* smem) {
;     ...
;       int im = (int)0x80000000;
; #pragma unroll
;       for (int r = 0; r < 16; ++r) im = max(im, max(__float_as_int(s0[r]), __float_as_int(s1[r])));
;       im = max(im, __shfl_xor(im, 32));
;       constexpr int TBITS = 0x41800000;
;       f32x16 e0, e1;
; #pragma unroll
;       for (int r = 0; r < 16; ++r) { e0[r] = ex2(s0[r]); e1[r] = ex2(s1[r]); }
;       if (__any(im > TBITS)) {
;         const float d = im > TBITS ? __int_as_float(im) : 0.f;
;         const float a = ex2(-d);
; #pragma unroll
;         for (int r = 0; r < 16; ++r) { e0[r] = ex2(s0[r] - d); e1[r] = ex2(s1[r] - d); st.o[0][r] *= a; st.o[1][r] *= a; }
;         st.l *= a; st.m += d;
; #pragma unroll
;         for (int r = 0; r < 16; ++r) st.mr[r] = -st.m;
;       }
.LBB0_641:
	s_nop 8
	v_max3_i32 v2, v113, v97, v112
	v_max3_i32 v3, v96, v114, v98
	v_max3_i32 v2, v2, v115, v99
	v_max3_i32 v3, v3, v116, v100
	v_max3_i32 v2, v2, v117, v101
	v_max3_i32 v3, v3, v118, v102
	v_max3_i32 v2, v2, v119, v103
	v_max3_i32 v3, v3, v120, v104
	v_max3_i32 v2, v2, v121, v105
	v_max3_i32 v3, v3, v122, v106
	v_max3_i32 v2, v2, v123, v107
	v_max3_i32 v3, v3, v124, v108
	v_max3_i32 v2, v2, v125, v109
	v_max3_i32 v3, v3, v126, v110
	v_max3_i32 v2, v2, v127, v111
	v_max_i32_e32 v2, v2, v3
	v_mov_b32_e32 v3, v2
	s_nop 1
	v_permlane32_swap_b32_e32 v3, v2
	v_max_i32_e32 v2, v2, v3
	v_cmp_lt_i32_e32 vcc, s88, v2
	s_cbranch_vccz .LBB0_643
	s_nop 0
	v_cndmask_b32_e32 v81, 0, v2, vcc
	v_sub_f32_e32 v2, v112, v81
	v_exp_f32_e32 v194, v2
	v_sub_f32_e32 v2, v96, v81
	v_exp_f32_e32 v189, v2
	v_sub_f32_e32 v2, v113, v81
	v_exp_f32_e32 v192, v2
	v_sub_f32_e32 v2, v97, v81
	v_exp_f32_e32 v190, v2
	v_sub_f32_e32 v2, v114, v81
	v_exp_f32_e32 v191, v2
	v_sub_f32_e32 v2, v98, v81
	v_sub_f32_e32 v82, v124, v81
	v_exp_f32_e32 v114, v2
	v_sub_f32_e32 v2, v115, v81
	v_exp_f32_e32 v96, v82
	v_sub_f32_e32 v82, v108, v81
	v_exp_f32_e32 v193, v2
	v_sub_f32_e32 v2, v99, v81
	v_exp_f32_e32 v98, v82
	v_sub_f32_e32 v82, v125, v81
	v_exp_f32_e32 v115, v2
	v_sub_f32_e32 v2, v116, v81
	v_exp_f32_e32 v97, v82
	v_sub_f32_e32 v82, v109, v81
	v_exp_f32_e32 v112, v2
	v_sub_f32_e32 v2, v100, v81
	v_exp_f32_e32 v99, v82
	v_sub_f32_e32 v82, v126, v81
	v_exp_f32_e32 v8, v2
	v_sub_f32_e32 v2, v117, v81
	v_sub_f32_e32 v4, v103, v81
	v_exp_f32_e32 v100, v82
	v_sub_f32_e32 v82, v110, v81
	v_exp_f32_e64 v80, -v81
	v_exp_f32_e32 v113, v2
	v_sub_f32_e32 v2, v101, v81
	v_sub_f32_e32 v3, v102, v81
	v_exp_f32_e32 v7, v4
	v_sub_f32_e32 v4, v120, v81
	v_sub_f32_e32 v5, v121, v81
	v_sub_f32_e32 v12, v122, v81
	v_sub_f32_e32 v13, v123, v81
	v_exp_f32_e32 v102, v82
	v_sub_f32_e32 v82, v127, v81
	v_exp_f32_e32 v9, v2
	v_sub_f32_e32 v2, v118, v81
	v_exp_f32_e32 v6, v3
	v_sub_f32_e32 v3, v119, v81
	v_exp_f32_e32 v10, v4
	v_sub_f32_e32 v4, v104, v81
	v_exp_f32_e32 v11, v5
	v_sub_f32_e32 v5, v105, v81
	v_exp_f32_e32 v14, v12
	v_sub_f32_e32 v12, v106, v81
	v_exp_f32_e32 v15, v13
	v_sub_f32_e32 v13, v107, v81
	v_exp_f32_e32 v101, v82
	v_sub_f32_e32 v82, v111, v81
	v_exp_f32_e32 v2, v2
	v_exp_f32_e32 v3, v3
	v_exp_f32_e32 v4, v4
	v_exp_f32_e32 v5, v5
	v_exp_f32_e32 v12, v12
	v_exp_f32_e32 v13, v13
	v_exp_f32_e32 v103, v82
	v_add_f32_e32 v188, v188, v81
	v_pk_mul_f32 v[78:79], v[78:79], v[80:81] op_sel_hi:[1,0]
	v_pk_mul_f32 v[76:77], v[76:77], v[80:81] op_sel_hi:[1,0]
	v_pk_mul_f32 v[74:75], v[74:75], v[80:81] op_sel_hi:[1,0]
	v_pk_mul_f32 v[72:73], v[72:73], v[80:81] op_sel_hi:[1,0]
	v_pk_mul_f32 v[70:71], v[70:71], v[80:81] op_sel_hi:[1,0]
	v_pk_mul_f32 v[68:69], v[68:69], v[80:81] op_sel_hi:[1,0]
	v_pk_mul_f32 v[66:67], v[66:67], v[80:81] op_sel_hi:[1,0]
	v_pk_mul_f32 v[64:65], v[64:65], v[80:81] op_sel_hi:[1,0]
	v_pk_mul_f32 v[62:63], v[62:63], v[80:81] op_sel_hi:[1,0]
	v_pk_mul_f32 v[60:61], v[60:61], v[80:81] op_sel_hi:[1,0]
	v_pk_mul_f32 v[58:59], v[58:59], v[80:81] op_sel_hi:[1,0]
	v_pk_mul_f32 v[56:57], v[56:57], v[80:81] op_sel_hi:[1,0]
	v_pk_mul_f32 v[54:55], v[54:55], v[80:81] op_sel_hi:[1,0]
	v_pk_mul_f32 v[52:53], v[52:53], v[80:81] op_sel_hi:[1,0]
	v_pk_mul_f32 v[50:51], v[50:51], v[80:81] op_sel_hi:[1,0]
	v_pk_mul_f32 v[48:49], v[48:49], v[80:81] op_sel_hi:[1,0]
	v_mul_f32_e32 v169, v169, v80
	v_xor_b32_e32 v80, 0x80000000, v188
	v_mov_b32_e32 v81, v80
	v_mov_b32_e32 v82, v80
	v_mov_b32_e32 v83, v80
	v_mov_b32_e32 v84, v80
	v_mov_b32_e32 v85, v80
	v_mov_b32_e32 v86, v80
	v_mov_b32_e32 v87, v80
	v_mov_b32_e32 v88, v80
	v_mov_b32_e32 v89, v80
	v_mov_b32_e32 v90, v80
	v_mov_b32_e32 v91, v80
	v_mov_b32_e32 v92, v80
	v_mov_b32_e32 v93, v80
	v_mov_b32_e32 v94, v80
	v_mov_b32_e32 v95, v80
	s_branch .LBB0_644

; DI float ex2(float x) { return __builtin_amdgcn_exp2f(x); }
; template <int MODE>
; DI void flash_pass(AState& st, const bf16x8* qf, u64 tmask, u64 wmask,
;                    const bf16_t* kbase, size_t kld, const bf16_t* kpe, const bf16_t* vtbase, const float* fbias,
;                    int tq, u64 mysel, bf16_t* smem) {
;     ...
;       int im = (int)0x80000000;
; #pragma unroll
;       for (int r = 0; r < 16; ++r) im = max(im, max(__float_as_int(s0[r]), __float_as_int(s1[r])));
;       im = max(im, __shfl_xor(im, 32));
;       constexpr int TBITS = 0x41800000;
;       f32x16 e0, e1;
; #pragma unroll
;       for (int r = 0; r < 16; ++r) { e0[r] = ex2(s0[r]); e1[r] = ex2(s1[r]); }
;       if (__any(im > TBITS)) {
;         const float d = im > TBITS ? __int_as_float(im) : 0.f;
;         const float a = ex2(-d);
; #pragma unroll
;         for (int r = 0; r < 16; ++r) { e0[r] = ex2(s0[r] - d); e1[r] = ex2(s1[r] - d); st.o[0][r] *= a; st.o[1][r] *= a; }
;         st.l *= a; st.m += d;
; #pragma unroll
;         for (int r = 0; r < 16; ++r) st.mr[r] = -st.m;
;       }
.LBB0_675:
	v_max3_i32 v90, v157, v161, v156
	v_max3_i32 v91, v160, v158, v96
	v_max3_i32 v90, v90, v159, v97
	v_max3_i32 v91, v91, v14, v10
	v_max3_i32 v90, v90, v15, v11
	v_max3_i32 v91, v91, v84, v80
	v_max3_i32 v90, v90, v85, v81
	v_max3_i32 v91, v91, v88, v86
	v_max3_i32 v90, v90, v89, v87
	v_max3_i32 v91, v91, v82, v12
	v_max3_i32 v90, v90, v83, v13
	v_max3_i32 v91, v91, v8, v6
	v_max3_i32 v90, v90, v9, v7
	v_max3_i32 v91, v91, v2, v4
	v_max3_i32 v90, v90, v3, v5
	v_max_i32_e32 v90, v90, v91
	v_mov_b32_e32 v91, v90
	s_nop 1
	v_permlane32_swap_b32_e32 v91, v90
	v_max_i32_e32 v90, v90, v91
	v_cmp_lt_i32_e32 vcc, s88, v90
	s_cbranch_vccz .LBB0_704
	s_nop 0
	v_cndmask_b32_e32 v65, 0, v90, vcc
	v_sub_f32_e32 v66, v156, v65
	v_exp_f32_e32 v98, v66
	v_sub_f32_e32 v66, v160, v65
	v_sub_f32_e32 v14, v14, v65
	v_sub_f32_e32 v10, v10, v65
	v_exp_f32_e32 v94, v66
	v_sub_f32_e32 v66, v157, v65
	v_exp_f32_e32 v90, v14
	v_exp_f32_e32 v14, v10
	v_sub_f32_e32 v10, v15, v65
	v_exp_f32_e32 v99, v66
	v_sub_f32_e32 v66, v161, v65
	v_exp_f32_e32 v91, v10
	v_sub_f32_e32 v10, v11, v65
	v_exp_f32_e32 v95, v66
	v_sub_f32_e32 v66, v158, v65
	v_exp_f32_e32 v15, v10
	v_sub_f32_e32 v10, v84, v65
	v_exp_f32_e32 v100, v66
	v_sub_f32_e32 v66, v96, v65
	v_exp_f32_e32 v92, v10
	v_sub_f32_e32 v10, v80, v65
	v_exp_f32_e32 v96, v66
	v_sub_f32_e32 v66, v159, v65
	v_exp_f32_e32 v80, v10
	v_sub_f32_e32 v10, v85, v65
	v_exp_f32_e32 v101, v66
	v_sub_f32_e32 v66, v97, v65
	v_exp_f32_e32 v93, v10
	v_sub_f32_e32 v10, v81, v65
	v_exp_f32_e64 v64, -v65
	v_exp_f32_e32 v97, v66
	v_exp_f32_e32 v81, v10
	v_sub_f32_e32 v10, v88, v65
	v_sub_f32_e32 v11, v89, v65
	v_sub_f32_e32 v66, v82, v65
	v_sub_f32_e32 v2, v2, v65
	v_sub_f32_e32 v3, v3, v65
	v_exp_f32_e32 v84, v10
	v_sub_f32_e32 v10, v86, v65
	v_exp_f32_e32 v85, v11
	v_sub_f32_e32 v11, v87, v65
	v_exp_f32_e32 v82, v66
	v_sub_f32_e32 v12, v12, v65
	v_sub_f32_e32 v66, v83, v65
	v_sub_f32_e32 v13, v13, v65
	v_sub_f32_e32 v8, v8, v65
	v_sub_f32_e32 v6, v6, v65
	v_sub_f32_e32 v9, v9, v65
	v_sub_f32_e32 v7, v7, v65
	v_exp_f32_e32 v86, v2
	v_sub_f32_e32 v2, v4, v65
	v_exp_f32_e32 v87, v3
	v_sub_f32_e32 v3, v5, v65
	v_exp_f32_e32 v10, v10
	v_exp_f32_e32 v11, v11
	v_exp_f32_e32 v12, v12
	v_exp_f32_e32 v83, v66
	v_exp_f32_e32 v13, v13
	v_exp_f32_e32 v8, v8
	v_exp_f32_e32 v6, v6
	v_exp_f32_e32 v9, v9
	v_exp_f32_e32 v7, v7
	v_exp_f32_e32 v2, v2
	v_exp_f32_e32 v3, v3
	v_add_f32_e32 v177, v177, v65
	v_pk_mul_f32 v[46:47], v[46:47], v[64:65] op_sel_hi:[1,0]
	v_pk_mul_f32 v[44:45], v[44:45], v[64:65] op_sel_hi:[1,0]
	v_pk_mul_f32 v[42:43], v[42:43], v[64:65] op_sel_hi:[1,0]
	v_pk_mul_f32 v[40:41], v[40:41], v[64:65] op_sel_hi:[1,0]
	v_pk_mul_f32 v[38:39], v[38:39], v[64:65] op_sel_hi:[1,0]
	v_pk_mul_f32 v[36:37], v[36:37], v[64:65] op_sel_hi:[1,0]
	v_pk_mul_f32 v[34:35], v[34:35], v[64:65] op_sel_hi:[1,0]
	v_pk_mul_f32 v[32:33], v[32:33], v[64:65] op_sel_hi:[1,0]
	v_pk_mul_f32 v[30:31], v[30:31], v[64:65] op_sel_hi:[1,0]
	v_pk_mul_f32 v[28:29], v[28:29], v[64:65] op_sel_hi:[1,0]
	v_pk_mul_f32 v[26:27], v[26:27], v[64:65] op_sel_hi:[1,0]
	v_pk_mul_f32 v[24:25], v[24:25], v[64:65] op_sel_hi:[1,0]
	v_pk_mul_f32 v[22:23], v[22:23], v[64:65] op_sel_hi:[1,0]
	v_pk_mul_f32 v[20:21], v[20:21], v[64:65] op_sel_hi:[1,0]
	v_pk_mul_f32 v[18:19], v[18:19], v[64:65] op_sel_hi:[1,0]
	v_pk_mul_f32 v[16:17], v[16:17], v[64:65] op_sel_hi:[1,0]
	v_mul_f32_e32 v176, v176, v64
	v_xor_b32_e32 v64, 0x80000000, v177
	v_mov_b32_e32 v65, v64
	v_mov_b32_e32 v66, v64
	v_mov_b32_e32 v67, v64
	v_mov_b32_e32 v68, v64
	v_mov_b32_e32 v69, v64
	v_mov_b32_e32 v70, v64
	v_mov_b32_e32 v71, v64
	v_mov_b32_e32 v72, v64
	v_mov_b32_e32 v73, v64
	v_mov_b32_e32 v74, v64
	v_mov_b32_e32 v75, v64
	v_mov_b32_e32 v76, v64
	v_mov_b32_e32 v77, v64
	v_mov_b32_e32 v78, v64
	v_mov_b32_e32 v79, v64

; DI float ex2(float x) { return __builtin_amdgcn_exp2f(x); }
; template <int MODE>
; DI void flash_pass(AState& st, const bf16x8* qf, u64 tmask, u64 wmask,
;                    const bf16_t* kbase, size_t kld, const bf16_t* kpe, const bf16_t* vtbase, const float* fbias,
;                    int tq, u64 mysel, bf16_t* smem) {
;     ...
;       int im = (int)0x80000000;
; #pragma unroll
;       for (int r = 0; r < 16; ++r) im = max(im, max(__float_as_int(s0[r]), __float_as_int(s1[r])));
;       im = max(im, __shfl_xor(im, 32));
;       constexpr int TBITS = 0x41800000;
;       f32x16 e0, e1;
; #pragma unroll
;       for (int r = 0; r < 16; ++r) { e0[r] = ex2(s0[r]); e1[r] = ex2(s1[r]); }
;       if (__any(im > TBITS)) {
;         const float d = im > TBITS ? __int_as_float(im) : 0.f;
;         const float a = ex2(-d);
; #pragma unroll
;         for (int r = 0; r < 16; ++r) { e0[r] = ex2(s0[r] - d); e1[r] = ex2(s1[r] - d); st.o[0][r] *= a; st.o[1][r] *= a; }
;         st.l *= a; st.m += d;
; #pragma unroll
;         for (int r = 0; r < 16; ++r) st.mr[r] = -st.m;
;       }
.LBB0_689:
	v_max3_i32 v90, v157, v161, v156
	v_max3_i32 v91, v160, v158, v96
	v_max3_i32 v90, v90, v159, v97
	v_max3_i32 v91, v91, v14, v10
	v_max3_i32 v90, v90, v15, v11
	v_max3_i32 v91, v91, v84, v80
	v_max3_i32 v90, v90, v85, v81
	v_max3_i32 v91, v91, v88, v86
	v_max3_i32 v90, v90, v89, v87
	v_max3_i32 v91, v91, v82, v12
	v_max3_i32 v90, v90, v83, v13
	v_max3_i32 v91, v91, v8, v6
	v_max3_i32 v90, v90, v9, v7
	v_max3_i32 v91, v91, v2, v4
	v_max3_i32 v90, v90, v3, v5
	v_max_i32_e32 v90, v90, v91
	v_mov_b32_e32 v91, v90
	s_nop 1
	v_permlane32_swap_b32_e32 v91, v90
	v_max_i32_e32 v90, v90, v91
	v_cmp_lt_i32_e32 vcc, s88, v90
	s_cbranch_vccz .LBB0_691
	s_nop 0
	v_cndmask_b32_e32 v65, 0, v90, vcc
	v_sub_f32_e32 v66, v156, v65
	v_exp_f32_e32 v98, v66
	v_sub_f32_e32 v66, v160, v65
	v_sub_f32_e32 v14, v14, v65
	v_sub_f32_e32 v10, v10, v65
	v_exp_f32_e32 v94, v66
	v_sub_f32_e32 v66, v157, v65
	v_exp_f32_e32 v90, v14
	v_exp_f32_e32 v14, v10
	v_sub_f32_e32 v10, v15, v65
	v_exp_f32_e32 v99, v66
	v_sub_f32_e32 v66, v161, v65
	v_exp_f32_e32 v91, v10
	v_sub_f32_e32 v10, v11, v65
	v_exp_f32_e32 v95, v66
	v_sub_f32_e32 v66, v158, v65
	v_exp_f32_e32 v15, v10
	v_sub_f32_e32 v10, v84, v65
	v_exp_f32_e32 v100, v66
	v_sub_f32_e32 v66, v96, v65
	v_exp_f32_e32 v92, v10
	v_sub_f32_e32 v10, v80, v65
	v_exp_f32_e32 v96, v66
	v_sub_f32_e32 v66, v159, v65
	v_exp_f32_e32 v80, v10
	v_sub_f32_e32 v10, v85, v65
	v_exp_f32_e32 v101, v66
	v_sub_f32_e32 v66, v97, v65
	v_exp_f32_e32 v93, v10
	v_sub_f32_e32 v10, v81, v65
	v_exp_f32_e64 v64, -v65
	v_exp_f32_e32 v97, v66
	v_exp_f32_e32 v81, v10
	v_sub_f32_e32 v10, v88, v65
	v_sub_f32_e32 v11, v89, v65
	v_sub_f32_e32 v66, v82, v65
	v_sub_f32_e32 v2, v2, v65
	v_sub_f32_e32 v3, v3, v65
	v_exp_f32_e32 v84, v10
	v_sub_f32_e32 v10, v86, v65
	v_exp_f32_e32 v85, v11
	v_sub_f32_e32 v11, v87, v65
	v_exp_f32_e32 v82, v66
	v_sub_f32_e32 v12, v12, v65
	v_sub_f32_e32 v66, v83, v65
	v_sub_f32_e32 v13, v13, v65
	v_sub_f32_e32 v8, v8, v65
	v_sub_f32_e32 v6, v6, v65
	v_sub_f32_e32 v9, v9, v65
	v_sub_f32_e32 v7, v7, v65
	v_exp_f32_e32 v86, v2
	v_sub_f32_e32 v2, v4, v65
	v_exp_f32_e32 v87, v3
	v_sub_f32_e32 v3, v5, v65
	v_exp_f32_e32 v10, v10
	v_exp_f32_e32 v11, v11
	v_exp_f32_e32 v12, v12
	v_exp_f32_e32 v83, v66
	v_exp_f32_e32 v13, v13
	v_exp_f32_e32 v8, v8
	v_exp_f32_e32 v6, v6
	v_exp_f32_e32 v9, v9
	v_exp_f32_e32 v7, v7
	v_exp_f32_e32 v2, v2
	v_exp_f32_e32 v3, v3
	v_add_f32_e32 v177, v177, v65
	v_pk_mul_f32 v[46:47], v[46:47], v[64:65] op_sel_hi:[1,0]
	v_pk_mul_f32 v[44:45], v[44:45], v[64:65] op_sel_hi:[1,0]
	v_pk_mul_f32 v[42:43], v[42:43], v[64:65] op_sel_hi:[1,0]
	v_pk_mul_f32 v[40:41], v[40:41], v[64:65] op_sel_hi:[1,0]
	v_pk_mul_f32 v[38:39], v[38:39], v[64:65] op_sel_hi:[1,0]
	v_pk_mul_f32 v[36:37], v[36:37], v[64:65] op_sel_hi:[1,0]
	v_pk_mul_f32 v[34:35], v[34:35], v[64:65] op_sel_hi:[1,0]
	v_pk_mul_f32 v[32:33], v[32:33], v[64:65] op_sel_hi:[1,0]
	v_pk_mul_f32 v[30:31], v[30:31], v[64:65] op_sel_hi:[1,0]
	v_pk_mul_f32 v[28:29], v[28:29], v[64:65] op_sel_hi:[1,0]
	v_pk_mul_f32 v[26:27], v[26:27], v[64:65] op_sel_hi:[1,0]
	v_pk_mul_f32 v[24:25], v[24:25], v[64:65] op_sel_hi:[1,0]
	v_pk_mul_f32 v[22:23], v[22:23], v[64:65] op_sel_hi:[1,0]
	v_pk_mul_f32 v[20:21], v[20:21], v[64:65] op_sel_hi:[1,0]
	v_pk_mul_f32 v[18:19], v[18:19], v[64:65] op_sel_hi:[1,0]
	v_pk_mul_f32 v[16:17], v[16:17], v[64:65] op_sel_hi:[1,0]
	v_mul_f32_e32 v176, v176, v64
	v_xor_b32_e32 v64, 0x80000000, v177
	v_mov_b32_e32 v65, v64
	v_mov_b32_e32 v66, v64
	v_mov_b32_e32 v67, v64
	v_mov_b32_e32 v68, v64
	v_mov_b32_e32 v69, v64
	v_mov_b32_e32 v70, v64
	v_mov_b32_e32 v71, v64
	v_mov_b32_e32 v72, v64
	v_mov_b32_e32 v73, v64
	v_mov_b32_e32 v74, v64
	v_mov_b32_e32 v75, v64
	v_mov_b32_e32 v76, v64
	v_mov_b32_e32 v77, v64
	v_mov_b32_e32 v78, v64
	v_mov_b32_e32 v79, v64
	s_branch .LBB0_692

; DI float ex2(float x) { return __builtin_amdgcn_exp2f(x); }
; template <int MODE>
; DI void flash_pass(AState& st, const bf16x8* qf, u64 tmask, u64 wmask,
;                    const bf16_t* kbase, size_t kld, const bf16_t* kpe, const bf16_t* vtbase, const float* fbias,
;                    int tq, u64 mysel, bf16_t* smem) {
;     ...
;       int im = (int)0x80000000;
; #pragma unroll
;       for (int r = 0; r < 16; ++r) im = max(im, max(__float_as_int(s0[r]), __float_as_int(s1[r])));
;       im = max(im, __shfl_xor(im, 32));
;       constexpr int TBITS = 0x41800000;
;       f32x16 e0, e1;
; #pragma unroll
;       for (int r = 0; r < 16; ++r) { e0[r] = ex2(s0[r]); e1[r] = ex2(s1[r]); }
;       if (__any(im > TBITS)) {
;         const float d = im > TBITS ? __int_as_float(im) : 0.f;
;         const float a = ex2(-d);
; #pragma unroll
;         for (int r = 0; r < 16; ++r) { e0[r] = ex2(s0[r] - d); e1[r] = ex2(s1[r] - d); st.o[0][r] *= a; st.o[1][r] *= a; }
;         st.l *= a; st.m += d;
; #pragma unroll
;         for (int r = 0; r < 16; ++r) st.mr[r] = -st.m;
;       }
.LBB0_757:
	s_nop 10
	v_max3_i32 v2, v81, v65, v80
	v_max3_i32 v3, v64, v82, v66
	v_max3_i32 v2, v2, v83, v67
	v_max3_i32 v3, v3, v84, v68
	v_max3_i32 v2, v2, v85, v69
	v_max3_i32 v3, v3, v86, v70
	v_max3_i32 v2, v2, v87, v71
	v_max3_i32 v3, v3, v88, v72
	v_max3_i32 v2, v2, v89, v73
	v_max3_i32 v3, v3, v90, v74
	v_max3_i32 v2, v2, v91, v75
	v_max3_i32 v3, v3, v92, v76
	v_max3_i32 v2, v2, v93, v77
	v_max3_i32 v3, v3, v94, v78
	v_max3_i32 v2, v2, v95, v79
	v_max_i32_e32 v2, v2, v3
	v_mov_b32_e32 v3, v2
	s_nop 1
	v_permlane32_swap_b32_e32 v3, v2
	v_max_i32_e32 v2, v2, v3
	v_cmp_lt_i32_e32 vcc, s88, v2
	s_cbranch_vccz .LBB0_759
	s_nop 0
	v_cndmask_b32_e32 v49, 0, v2, vcc
	v_sub_f32_e32 v2, v80, v49
	v_exp_f32_e32 v183, v2
	v_sub_f32_e32 v2, v64, v49
	v_exp_f32_e32 v178, v2
	v_sub_f32_e32 v2, v81, v49
	v_exp_f32_e32 v181, v2
	v_sub_f32_e32 v2, v65, v49
	v_exp_f32_e32 v179, v2
	v_sub_f32_e32 v2, v82, v49
	v_exp_f32_e32 v180, v2
	v_sub_f32_e32 v2, v66, v49
	v_sub_f32_e32 v50, v92, v49
	v_exp_f32_e32 v82, v2
	v_sub_f32_e32 v2, v83, v49
	v_exp_f32_e32 v64, v50
	v_sub_f32_e32 v50, v76, v49
	v_exp_f32_e32 v182, v2
	v_sub_f32_e32 v2, v67, v49
	v_exp_f32_e32 v66, v50
	v_sub_f32_e32 v50, v93, v49
	v_exp_f32_e32 v83, v2
	v_sub_f32_e32 v2, v84, v49
	v_exp_f32_e32 v65, v50
	v_sub_f32_e32 v50, v77, v49
	v_exp_f32_e32 v80, v2
	v_sub_f32_e32 v2, v68, v49
	v_exp_f32_e32 v67, v50
	v_sub_f32_e32 v50, v94, v49
	v_exp_f32_e32 v8, v2
	v_sub_f32_e32 v2, v85, v49
	v_sub_f32_e32 v4, v71, v49
	v_exp_f32_e32 v68, v50
	v_sub_f32_e32 v50, v78, v49
	v_exp_f32_e64 v48, -v49
	v_exp_f32_e32 v81, v2
	v_sub_f32_e32 v2, v69, v49
	v_sub_f32_e32 v3, v70, v49
	v_exp_f32_e32 v7, v4
	v_sub_f32_e32 v4, v88, v49
	v_sub_f32_e32 v5, v89, v49
	v_sub_f32_e32 v12, v90, v49
	v_sub_f32_e32 v13, v91, v49
	v_exp_f32_e32 v70, v50
	v_sub_f32_e32 v50, v95, v49
	v_exp_f32_e32 v9, v2
	v_sub_f32_e32 v2, v86, v49
	v_exp_f32_e32 v6, v3
	v_sub_f32_e32 v3, v87, v49
	v_exp_f32_e32 v10, v4
	v_sub_f32_e32 v4, v72, v49
	v_exp_f32_e32 v11, v5
	v_sub_f32_e32 v5, v73, v49
	v_exp_f32_e32 v14, v12
	v_sub_f32_e32 v12, v74, v49
	v_exp_f32_e32 v15, v13
	v_sub_f32_e32 v13, v75, v49
	v_exp_f32_e32 v69, v50
	v_sub_f32_e32 v50, v79, v49
	v_exp_f32_e32 v2, v2
	v_exp_f32_e32 v3, v3
	v_exp_f32_e32 v4, v4
	v_exp_f32_e32 v5, v5
	v_exp_f32_e32 v12, v12
	v_exp_f32_e32 v13, v13
	v_exp_f32_e32 v71, v50
	v_add_f32_e32 v0, v0, v49
	v_pk_mul_f32 v[46:47], v[46:47], v[48:49] op_sel_hi:[1,0]
	v_pk_mul_f32 v[44:45], v[44:45], v[48:49] op_sel_hi:[1,0]
	v_pk_mul_f32 v[42:43], v[42:43], v[48:49] op_sel_hi:[1,0]
	v_pk_mul_f32 v[40:41], v[40:41], v[48:49] op_sel_hi:[1,0]
	v_pk_mul_f32 v[38:39], v[38:39], v[48:49] op_sel_hi:[1,0]
	v_pk_mul_f32 v[36:37], v[36:37], v[48:49] op_sel_hi:[1,0]
	v_pk_mul_f32 v[34:35], v[34:35], v[48:49] op_sel_hi:[1,0]
	v_pk_mul_f32 v[32:33], v[32:33], v[48:49] op_sel_hi:[1,0]
	v_pk_mul_f32 v[30:31], v[30:31], v[48:49] op_sel_hi:[1,0]
	v_pk_mul_f32 v[28:29], v[28:29], v[48:49] op_sel_hi:[1,0]
	v_pk_mul_f32 v[26:27], v[26:27], v[48:49] op_sel_hi:[1,0]
	v_pk_mul_f32 v[24:25], v[24:25], v[48:49] op_sel_hi:[1,0]
	v_pk_mul_f32 v[22:23], v[22:23], v[48:49] op_sel_hi:[1,0]
	v_pk_mul_f32 v[20:21], v[20:21], v[48:49] op_sel_hi:[1,0]
	v_pk_mul_f32 v[18:19], v[18:19], v[48:49] op_sel_hi:[1,0]
	v_pk_mul_f32 v[16:17], v[16:17], v[48:49] op_sel_hi:[1,0]
	v_mul_f32_e32 v171, v171, v48
	v_xor_b32_e32 v48, 0x80000000, v0
	v_mov_b32_e32 v49, v48
	v_mov_b32_e32 v50, v48
	v_mov_b32_e32 v51, v48
	v_mov_b32_e32 v52, v48
	v_mov_b32_e32 v53, v48
	v_mov_b32_e32 v54, v48
	v_mov_b32_e32 v55, v48
	v_mov_b32_e32 v56, v48
	v_mov_b32_e32 v57, v48
	v_mov_b32_e32 v58, v48
	v_mov_b32_e32 v59, v48
	v_mov_b32_e32 v60, v48
	v_mov_b32_e32 v61, v48
	v_mov_b32_e32 v62, v48
	v_mov_b32_e32 v63, v48
	s_branch .LBB0_760

; DI float ex2(float x) { return __builtin_amdgcn_exp2f(x); }
; template <int MODE>
; DI void flash_pass(AState& st, const bf16x8* qf, u64 tmask, u64 wmask,
;                    const bf16_t* kbase, size_t kld, const bf16_t* kpe, const bf16_t* vtbase, const float* fbias,
;                    int tq, u64 mysel, bf16_t* smem) {
;     ...
;       int im = (int)0x80000000;
; #pragma unroll
;       for (int r = 0; r < 16; ++r) im = max(im, max(__float_as_int(s0[r]), __float_as_int(s1[r])));
;       im = max(im, __shfl_xor(im, 32));
;       constexpr int TBITS = 0x41800000;
;       f32x16 e0, e1;
; #pragma unroll
;       for (int r = 0; r < 16; ++r) { e0[r] = ex2(s0[r]); e1[r] = ex2(s1[r]); }
;       if (__any(im > TBITS)) {
;         const float d = im > TBITS ? __int_as_float(im) : 0.f;
;         const float a = ex2(-d);
; #pragma unroll
;         for (int r = 0; r < 16; ++r) { e0[r] = ex2(s0[r] - d); e1[r] = ex2(s1[r] - d); st.o[0][r] *= a; st.o[1][r] *= a; }
;         st.l *= a; st.m += d;
; #pragma unroll
;         for (int r = 0; r < 16; ++r) st.mr[r] = -st.m;
;       }
.LBB0_769:
	s_nop 10
	v_max3_i32 v2, v81, v65, v80
	v_max3_i32 v3, v64, v82, v66
	v_max3_i32 v2, v2, v83, v67
	v_max3_i32 v3, v3, v84, v68
	v_max3_i32 v2, v2, v85, v69
	v_max3_i32 v3, v3, v86, v70
	v_max3_i32 v2, v2, v87, v71
	v_max3_i32 v3, v3, v88, v72
	v_max3_i32 v2, v2, v89, v73
	v_max3_i32 v3, v3, v90, v74
	v_max3_i32 v2, v2, v91, v75
	v_max3_i32 v3, v3, v92, v76
	v_max3_i32 v2, v2, v93, v77
	v_max3_i32 v3, v3, v94, v78
	v_max3_i32 v2, v2, v95, v79
	v_max_i32_e32 v2, v2, v3
	v_mov_b32_e32 v3, v2
	s_nop 1
	v_permlane32_swap_b32_e32 v3, v2
	v_max_i32_e32 v2, v2, v3
	v_cmp_lt_i32_e32 vcc, s88, v2
	s_cbranch_vccz .LBB0_771
	s_nop 0
	v_cndmask_b32_e32 v49, 0, v2, vcc
	v_sub_f32_e32 v2, v80, v49
	v_exp_f32_e32 v179, v2
	v_sub_f32_e32 v2, v64, v49
	v_exp_f32_e32 v177, v2
	v_sub_f32_e32 v2, v81, v49
	v_exp_f32_e32 v180, v2
	v_sub_f32_e32 v2, v65, v49
	v_exp_f32_e32 v178, v2
	v_sub_f32_e32 v2, v82, v49
	v_exp_f32_e32 v181, v2
	v_sub_f32_e32 v2, v66, v49
	v_exp_f32_e32 v82, v2
	v_sub_f32_e32 v2, v83, v49
	v_exp_f32_e32 v182, v2
	v_sub_f32_e32 v2, v67, v49
	v_exp_f32_e32 v83, v2
	v_sub_f32_e32 v2, v84, v49
	v_exp_f32_e32 v66, v2
	v_sub_f32_e32 v2, v68, v49
	v_exp_f32_e32 v10, v2
	v_sub_f32_e32 v2, v85, v49
	v_exp_f32_e32 v67, v2
	v_sub_f32_e32 v2, v69, v49
	v_exp_f32_e32 v11, v2
	v_sub_f32_e32 v2, v86, v49
	v_exp_f32_e32 v80, v2
	v_sub_f32_e32 v2, v70, v49
	v_exp_f32_e32 v12, v2
	v_sub_f32_e32 v2, v87, v49
	v_exp_f32_e32 v81, v2
	v_sub_f32_e32 v2, v71, v49
	v_exp_f32_e64 v48, -v49
	v_exp_f32_e32 v13, v2
	v_sub_f32_e32 v2, v88, v49
	v_sub_f32_e32 v3, v89, v49
	v_sub_f32_e32 v4, v90, v49
	v_sub_f32_e32 v5, v91, v49
	v_sub_f32_e32 v6, v92, v49
	v_sub_f32_e32 v7, v93, v49
	v_sub_f32_e32 v8, v94, v49
	v_sub_f32_e32 v9, v95, v49
	v_exp_f32_e32 v14, v2
	v_sub_f32_e32 v2, v72, v49
	v_exp_f32_e32 v15, v3
	v_sub_f32_e32 v3, v73, v49
	v_exp_f32_e32 v64, v4
	v_sub_f32_e32 v4, v74, v49
	v_exp_f32_e32 v65, v5
	v_sub_f32_e32 v5, v75, v49
	v_exp_f32_e32 v68, v6
	v_sub_f32_e32 v6, v76, v49
	v_exp_f32_e32 v69, v7
	v_sub_f32_e32 v7, v77, v49
	v_exp_f32_e32 v70, v8
	v_sub_f32_e32 v8, v78, v49
	v_exp_f32_e32 v71, v9
	v_sub_f32_e32 v9, v79, v49
	v_exp_f32_e32 v2, v2
	v_exp_f32_e32 v3, v3
	v_exp_f32_e32 v4, v4
	v_exp_f32_e32 v5, v5
	v_exp_f32_e32 v6, v6
	v_exp_f32_e32 v7, v7
	v_exp_f32_e32 v8, v8
	v_exp_f32_e32 v9, v9
	v_add_f32_e32 v0, v0, v49
	v_pk_mul_f32 v[46:47], v[46:47], v[48:49] op_sel_hi:[1,0]
	v_pk_mul_f32 v[44:45], v[44:45], v[48:49] op_sel_hi:[1,0]
	v_pk_mul_f32 v[42:43], v[42:43], v[48:49] op_sel_hi:[1,0]
	v_pk_mul_f32 v[40:41], v[40:41], v[48:49] op_sel_hi:[1,0]
	v_pk_mul_f32 v[38:39], v[38:39], v[48:49] op_sel_hi:[1,0]
	v_pk_mul_f32 v[36:37], v[36:37], v[48:49] op_sel_hi:[1,0]
	v_pk_mul_f32 v[34:35], v[34:35], v[48:49] op_sel_hi:[1,0]
	v_pk_mul_f32 v[32:33], v[32:33], v[48:49] op_sel_hi:[1,0]
	v_pk_mul_f32 v[30:31], v[30:31], v[48:49] op_sel_hi:[1,0]
	v_pk_mul_f32 v[28:29], v[28:29], v[48:49] op_sel_hi:[1,0]
	v_pk_mul_f32 v[26:27], v[26:27], v[48:49] op_sel_hi:[1,0]
	v_pk_mul_f32 v[24:25], v[24:25], v[48:49] op_sel_hi:[1,0]
	v_pk_mul_f32 v[22:23], v[22:23], v[48:49] op_sel_hi:[1,0]
	v_pk_mul_f32 v[20:21], v[20:21], v[48:49] op_sel_hi:[1,0]
	v_pk_mul_f32 v[18:19], v[18:19], v[48:49] op_sel_hi:[1,0]
	v_pk_mul_f32 v[16:17], v[16:17], v[48:49] op_sel_hi:[1,0]
	v_mul_f32_e32 v171, v171, v48
	v_xor_b32_e32 v48, 0x80000000, v0
	v_mov_b32_e32 v49, v48
	v_mov_b32_e32 v50, v48
	v_mov_b32_e32 v51, v48
	v_mov_b32_e32 v52, v48
	v_mov_b32_e32 v53, v48
	v_mov_b32_e32 v54, v48
	v_mov_b32_e32 v55, v48
	v_mov_b32_e32 v56, v48
	v_mov_b32_e32 v57, v48
	v_mov_b32_e32 v58, v48
	v_mov_b32_e32 v59, v48
	v_mov_b32_e32 v60, v48
	v_mov_b32_e32 v61, v48
	v_mov_b32_e32 v62, v48
	v_mov_b32_e32 v63, v48
	s_branch .LBB0_772

; DI float ex2(float x) { return __builtin_amdgcn_exp2f(x); }
; template <int MODE>
; DI void flash_pass(AState& st, const bf16x8* qf, u64 tmask, u64 wmask,
;                    const bf16_t* kbase, size_t kld, const bf16_t* kpe, const bf16_t* vtbase, const float* fbias,
;                    int tq, u64 mysel, bf16_t* smem) {
;     ...
;       int im = (int)0x80000000;
; #pragma unroll
;       for (int r = 0; r < 16; ++r) im = max(im, max(__float_as_int(s0[r]), __float_as_int(s1[r])));
;       im = max(im, __shfl_xor(im, 32));
;       constexpr int TBITS = 0x41800000;
;       f32x16 e0, e1;
; #pragma unroll
;       for (int r = 0; r < 16; ++r) { e0[r] = ex2(s0[r]); e1[r] = ex2(s1[r]); }
;       if (__any(im > TBITS)) {
;         const float d = im > TBITS ? __int_as_float(im) : 0.f;
;         const float a = ex2(-d);
; #pragma unroll
;         for (int r = 0; r < 16; ++r) { e0[r] = ex2(s0[r] - d); e1[r] = ex2(s1[r] - d); st.o[0][r] *= a; st.o[1][r] *= a; }
;         st.l *= a; st.m += d;
; #pragma unroll
;         for (int r = 0; r < 16; ++r) st.mr[r] = -st.m;
;       }
.LBB0_1646:
	s_nop 10
	v_max3_i32 v2, v81, v65, v80
	v_max3_i32 v3, v64, v82, v66
	v_max3_i32 v2, v2, v83, v67
	v_max3_i32 v3, v3, v84, v68
	v_max3_i32 v2, v2, v85, v69
	v_max3_i32 v3, v3, v86, v70
	v_max3_i32 v2, v2, v87, v71
	v_max3_i32 v3, v3, v88, v72
	v_max3_i32 v2, v2, v89, v73
	v_max3_i32 v3, v3, v90, v74
	v_max3_i32 v2, v2, v91, v75
	v_max3_i32 v3, v3, v92, v76
	v_max3_i32 v2, v2, v93, v77
	v_max3_i32 v3, v3, v94, v78
	v_max3_i32 v2, v2, v95, v79
	v_max_i32_e32 v2, v2, v3
	v_mov_b32_e32 v3, v2
	s_nop 1
	v_permlane32_swap_b32_e32 v3, v2
	v_max_i32_e32 v2, v2, v3
	v_cmp_lt_i32_e32 vcc, s88, v2
	s_cbranch_vccz .LBB0_1648
	s_nop 0
	v_cndmask_b32_e32 v49, 0, v2, vcc
	v_sub_f32_e32 v2, v80, v49
	v_exp_f32_e32 v152, v2
	v_sub_f32_e32 v2, v64, v49
	v_exp_f32_e32 v147, v2
	v_sub_f32_e32 v2, v81, v49
	v_exp_f32_e32 v150, v2
	v_sub_f32_e32 v2, v65, v49
	v_exp_f32_e32 v148, v2
	v_sub_f32_e32 v2, v82, v49
	v_exp_f32_e32 v149, v2
	v_sub_f32_e32 v2, v66, v49
	v_sub_f32_e32 v50, v92, v49
	v_exp_f32_e32 v82, v2
	v_sub_f32_e32 v2, v83, v49
	v_exp_f32_e32 v64, v50
	v_sub_f32_e32 v50, v76, v49
	v_exp_f32_e32 v151, v2
	v_sub_f32_e32 v2, v67, v49
	v_exp_f32_e32 v66, v50
	v_sub_f32_e32 v50, v93, v49
	v_exp_f32_e32 v83, v2
	v_sub_f32_e32 v2, v84, v49
	v_exp_f32_e32 v65, v50
	v_sub_f32_e32 v50, v77, v49
	v_exp_f32_e32 v80, v2
	v_sub_f32_e32 v2, v68, v49
	v_exp_f32_e32 v67, v50
	v_sub_f32_e32 v50, v94, v49
	v_exp_f32_e32 v8, v2
	v_sub_f32_e32 v2, v85, v49
	v_sub_f32_e32 v4, v71, v49
	v_exp_f32_e32 v68, v50
	v_sub_f32_e32 v50, v78, v49
	v_exp_f32_e64 v48, -v49
	v_exp_f32_e32 v81, v2
	v_sub_f32_e32 v2, v69, v49
	v_sub_f32_e32 v3, v70, v49
	v_exp_f32_e32 v7, v4
	v_sub_f32_e32 v4, v88, v49
	v_sub_f32_e32 v5, v89, v49
	v_sub_f32_e32 v12, v90, v49
	v_sub_f32_e32 v13, v91, v49
	v_exp_f32_e32 v70, v50
	v_sub_f32_e32 v50, v95, v49
	v_exp_f32_e32 v9, v2
	v_sub_f32_e32 v2, v86, v49
	v_exp_f32_e32 v6, v3
	v_sub_f32_e32 v3, v87, v49
	v_exp_f32_e32 v10, v4
	v_sub_f32_e32 v4, v72, v49
	v_exp_f32_e32 v11, v5
	v_sub_f32_e32 v5, v73, v49
	v_exp_f32_e32 v14, v12
	v_sub_f32_e32 v12, v74, v49
	v_exp_f32_e32 v15, v13
	v_sub_f32_e32 v13, v75, v49
	v_exp_f32_e32 v69, v50
	v_sub_f32_e32 v50, v79, v49
	v_exp_f32_e32 v2, v2
	v_exp_f32_e32 v3, v3
	v_exp_f32_e32 v4, v4
	v_exp_f32_e32 v5, v5
	v_exp_f32_e32 v12, v12
	v_exp_f32_e32 v13, v13
	v_exp_f32_e32 v71, v50
	v_add_f32_e32 v146, v146, v49
	v_pk_mul_f32 v[46:47], v[46:47], v[48:49] op_sel_hi:[1,0]
	v_pk_mul_f32 v[44:45], v[44:45], v[48:49] op_sel_hi:[1,0]
	v_pk_mul_f32 v[42:43], v[42:43], v[48:49] op_sel_hi:[1,0]
	v_pk_mul_f32 v[40:41], v[40:41], v[48:49] op_sel_hi:[1,0]
	v_pk_mul_f32 v[38:39], v[38:39], v[48:49] op_sel_hi:[1,0]
	v_pk_mul_f32 v[36:37], v[36:37], v[48:49] op_sel_hi:[1,0]
	v_pk_mul_f32 v[34:35], v[34:35], v[48:49] op_sel_hi:[1,0]
	v_pk_mul_f32 v[32:33], v[32:33], v[48:49] op_sel_hi:[1,0]
	v_pk_mul_f32 v[30:31], v[30:31], v[48:49] op_sel_hi:[1,0]
	v_pk_mul_f32 v[28:29], v[28:29], v[48:49] op_sel_hi:[1,0]
	v_pk_mul_f32 v[26:27], v[26:27], v[48:49] op_sel_hi:[1,0]
	v_pk_mul_f32 v[24:25], v[24:25], v[48:49] op_sel_hi:[1,0]
	v_pk_mul_f32 v[22:23], v[22:23], v[48:49] op_sel_hi:[1,0]
	v_pk_mul_f32 v[20:21], v[20:21], v[48:49] op_sel_hi:[1,0]
	v_pk_mul_f32 v[18:19], v[18:19], v[48:49] op_sel_hi:[1,0]
	v_pk_mul_f32 v[16:17], v[16:17], v[48:49] op_sel_hi:[1,0]
	v_mul_f32_e32 v178, v178, v48
	v_xor_b32_e32 v48, 0x80000000, v146
	v_mov_b32_e32 v49, v48
	v_mov_b32_e32 v50, v48
	v_mov_b32_e32 v51, v48
	v_mov_b32_e32 v52, v48
	v_mov_b32_e32 v53, v48
	v_mov_b32_e32 v54, v48
	v_mov_b32_e32 v55, v48
	v_mov_b32_e32 v56, v48
	v_mov_b32_e32 v57, v48
	v_mov_b32_e32 v58, v48
	v_mov_b32_e32 v59, v48
	v_mov_b32_e32 v60, v48
	v_mov_b32_e32 v61, v48
	v_mov_b32_e32 v62, v48
	v_mov_b32_e32 v63, v48
	s_branch .LBB0_1649

; DI float ex2(float x) { return __builtin_amdgcn_exp2f(x); }
; template <int MODE>
; DI void flash_pass(AState& st, const bf16x8* qf, u64 tmask, u64 wmask,
;                    const bf16_t* kbase, size_t kld, const bf16_t* kpe, const bf16_t* vtbase, const float* fbias,
;                    int tq, u64 mysel, bf16_t* smem) {
;     ...
;       int im = (int)0x80000000;
; #pragma unroll
;       for (int r = 0; r < 16; ++r) im = max(im, max(__float_as_int(s0[r]), __float_as_int(s1[r])));
;       im = max(im, __shfl_xor(im, 32));
;       constexpr int TBITS = 0x41800000;
;       f32x16 e0, e1;
; #pragma unroll
;       for (int r = 0; r < 16; ++r) { e0[r] = ex2(s0[r]); e1[r] = ex2(s1[r]); }
;       if (__any(im > TBITS)) {
;         const float d = im > TBITS ? __int_as_float(im) : 0.f;
;         const float a = ex2(-d);
; #pragma unroll
;         for (int r = 0; r < 16; ++r) { e0[r] = ex2(s0[r] - d); e1[r] = ex2(s1[r] - d); st.o[0][r] *= a; st.o[1][r] *= a; }
;         st.l *= a; st.m += d;
; #pragma unroll
;         for (int r = 0; r < 16; ++r) st.mr[r] = -st.m;
;       }
.LBB0_1675:
	s_nop 8
	v_max3_i32 v2, v97, v113, v96
	v_max3_i32 v3, v112, v98, v114
	v_max3_i32 v2, v2, v99, v115
	v_max3_i32 v3, v3, v100, v116
	v_max3_i32 v2, v2, v101, v117
	v_max3_i32 v3, v3, v102, v118
	v_max3_i32 v2, v2, v103, v119
	v_max3_i32 v3, v3, v104, v120
	v_max3_i32 v2, v2, v105, v121
	v_max3_i32 v3, v3, v106, v122
	v_max3_i32 v2, v2, v107, v123
	v_max3_i32 v3, v3, v108, v124
	v_max3_i32 v2, v2, v109, v125
	v_max3_i32 v3, v3, v110, v126
	v_max3_i32 v2, v2, v111, v127
	v_max_i32_e32 v2, v2, v3
	v_mov_b32_e32 v3, v2
	s_nop 1
	v_permlane32_swap_b32_e32 v3, v2
	v_max_i32_e32 v2, v2, v3
	v_cmp_lt_i32_e32 vcc, s88, v2
	s_cbranch_vccz .LBB0_1677
	s_nop 0
	v_cndmask_b32_e32 v81, 0, v2, vcc
	v_sub_f32_e32 v2, v96, v81
	v_exp_f32_e32 v192, v2
	v_sub_f32_e32 v2, v112, v81
	v_exp_f32_e32 v112, v2
	v_sub_f32_e32 v2, v97, v81
	v_exp_f32_e32 v190, v2
	v_sub_f32_e32 v2, v113, v81
	v_exp_f32_e32 v113, v2
	v_sub_f32_e32 v2, v98, v81
	v_exp_f32_e32 v189, v2
	v_sub_f32_e32 v2, v114, v81
	v_exp_f32_e32 v114, v2
	v_sub_f32_e32 v2, v99, v81
	v_exp_f32_e32 v191, v2
	v_sub_f32_e32 v2, v115, v81
	v_sub_f32_e32 v82, v108, v81
	v_exp_f32_e32 v115, v2
	v_sub_f32_e32 v2, v100, v81
	v_exp_f32_e32 v96, v82
	v_sub_f32_e32 v82, v124, v81
	v_exp_f32_e32 v100, v2
	v_sub_f32_e32 v2, v116, v81
	v_exp_f32_e32 v98, v82
	v_sub_f32_e32 v82, v109, v81
	v_exp_f32_e32 v8, v2
	v_sub_f32_e32 v2, v101, v81
	v_exp_f32_e32 v97, v82
	v_sub_f32_e32 v82, v125, v81
	v_exp_f32_e32 v101, v2
	v_sub_f32_e32 v2, v117, v81
	v_exp_f32_e32 v99, v82
	v_sub_f32_e32 v82, v110, v81
	v_exp_f32_e32 v9, v2
	v_sub_f32_e32 v2, v102, v81
	v_sub_f32_e32 v4, v119, v81
	v_exp_f32_e32 v102, v82
	v_sub_f32_e32 v82, v126, v81
	v_exp_f32_e64 v80, -v81
	v_sub_f32_e32 v3, v118, v81
	v_exp_f32_e32 v7, v4
	v_sub_f32_e32 v4, v104, v81
	v_sub_f32_e32 v5, v105, v81
	v_sub_f32_e32 v12, v106, v81
	v_sub_f32_e32 v13, v107, v81
	v_exp_f32_e32 v104, v82
	v_sub_f32_e32 v82, v111, v81
	v_exp_f32_e32 v6, v3
	v_sub_f32_e32 v3, v103, v81
	v_exp_f32_e32 v10, v4
	v_sub_f32_e32 v4, v120, v81
	v_exp_f32_e32 v11, v5
	v_sub_f32_e32 v5, v121, v81
	v_exp_f32_e32 v14, v12
	v_sub_f32_e32 v12, v122, v81
	v_exp_f32_e32 v15, v13
	v_sub_f32_e32 v13, v123, v81
	v_exp_f32_e32 v103, v82
	v_sub_f32_e32 v82, v127, v81
	v_exp_f32_e32 v2, v2
	v_exp_f32_e32 v3, v3
	v_exp_f32_e32 v4, v4
	v_exp_f32_e32 v5, v5
	v_exp_f32_e32 v12, v12
	v_exp_f32_e32 v13, v13
	v_exp_f32_e32 v105, v82
	v_add_f32_e32 v188, v188, v81
	v_pk_mul_f32 v[78:79], v[78:79], v[80:81] op_sel_hi:[1,0]
	v_pk_mul_f32 v[76:77], v[76:77], v[80:81] op_sel_hi:[1,0]
	v_pk_mul_f32 v[74:75], v[74:75], v[80:81] op_sel_hi:[1,0]
	v_pk_mul_f32 v[72:73], v[72:73], v[80:81] op_sel_hi:[1,0]
	v_pk_mul_f32 v[70:71], v[70:71], v[80:81] op_sel_hi:[1,0]
	v_pk_mul_f32 v[68:69], v[68:69], v[80:81] op_sel_hi:[1,0]
	v_pk_mul_f32 v[66:67], v[66:67], v[80:81] op_sel_hi:[1,0]
	v_pk_mul_f32 v[64:65], v[64:65], v[80:81] op_sel_hi:[1,0]
	v_pk_mul_f32 v[62:63], v[62:63], v[80:81] op_sel_hi:[1,0]
	v_pk_mul_f32 v[60:61], v[60:61], v[80:81] op_sel_hi:[1,0]
	v_pk_mul_f32 v[58:59], v[58:59], v[80:81] op_sel_hi:[1,0]
	v_pk_mul_f32 v[56:57], v[56:57], v[80:81] op_sel_hi:[1,0]
	v_pk_mul_f32 v[54:55], v[54:55], v[80:81] op_sel_hi:[1,0]
	v_pk_mul_f32 v[52:53], v[52:53], v[80:81] op_sel_hi:[1,0]
	v_pk_mul_f32 v[50:51], v[50:51], v[80:81] op_sel_hi:[1,0]
	v_pk_mul_f32 v[48:49], v[48:49], v[80:81] op_sel_hi:[1,0]
	v_mul_f32_e32 v169, v169, v80
	v_xor_b32_e32 v80, 0x80000000, v188
	v_mov_b32_e32 v81, v80
	v_mov_b32_e32 v82, v80
	v_mov_b32_e32 v83, v80
	v_mov_b32_e32 v84, v80
	v_mov_b32_e32 v85, v80
	v_mov_b32_e32 v86, v80
	v_mov_b32_e32 v87, v80
	v_mov_b32_e32 v88, v80
	v_mov_b32_e32 v89, v80
	v_mov_b32_e32 v90, v80
	v_mov_b32_e32 v91, v80
	v_mov_b32_e32 v92, v80
	v_mov_b32_e32 v93, v80
	v_mov_b32_e32 v94, v80
	v_mov_b32_e32 v95, v80
	s_branch .LBB0_1678

; DI float ex2(float x) { return __builtin_amdgcn_exp2f(x); }
; template <int MODE>
; DI void flash_pass(AState& st, const bf16x8* qf, u64 tmask, u64 wmask,
;                    const bf16_t* kbase, size_t kld, const bf16_t* kpe, const bf16_t* vtbase, const float* fbias,
;                    int tq, u64 mysel, bf16_t* smem) {
;     ...
;       int im = (int)0x80000000;
; #pragma unroll
;       for (int r = 0; r < 16; ++r) im = max(im, max(__float_as_int(s0[r]), __float_as_int(s1[r])));
;       im = max(im, __shfl_xor(im, 32));
;       constexpr int TBITS = 0x41800000;
;       f32x16 e0, e1;
; #pragma unroll
;       for (int r = 0; r < 16; ++r) { e0[r] = ex2(s0[r]); e1[r] = ex2(s1[r]); }
;       if (__any(im > TBITS)) {
;         const float d = im > TBITS ? __int_as_float(im) : 0.f;
;         const float a = ex2(-d);
; #pragma unroll
;         for (int r = 0; r < 16; ++r) { e0[r] = ex2(s0[r] - d); e1[r] = ex2(s1[r] - d); st.o[0][r] *= a; st.o[1][r] *= a; }
;         st.l *= a; st.m += d;
; #pragma unroll
;         for (int r = 0; r < 16; ++r) st.mr[r] = -st.m;
;       }
.LBB0_1709:
	v_max3_i32 v90, v157, v161, v156
	v_max3_i32 v91, v160, v158, v96
	v_max3_i32 v90, v90, v159, v97
	v_max3_i32 v91, v91, v14, v10
	v_max3_i32 v90, v90, v15, v11
	v_max3_i32 v91, v91, v84, v80
	v_max3_i32 v90, v90, v85, v81
	v_max3_i32 v91, v91, v88, v86
	v_max3_i32 v90, v90, v89, v87
	v_max3_i32 v91, v91, v82, v12
	v_max3_i32 v90, v90, v83, v13
	v_max3_i32 v91, v91, v8, v6
	v_max3_i32 v90, v90, v9, v7
	v_max3_i32 v91, v91, v2, v4
	v_max3_i32 v90, v90, v3, v5
	v_max_i32_e32 v90, v90, v91
	v_mov_b32_e32 v91, v90
	s_nop 1
	v_permlane32_swap_b32_e32 v91, v90
	v_max_i32_e32 v90, v90, v91
	v_cmp_lt_i32_e32 vcc, s88, v90
	s_cbranch_vccz .LBB0_1738
	s_nop 0
	v_cndmask_b32_e32 v65, 0, v90, vcc
	v_sub_f32_e32 v66, v156, v65
	v_exp_f32_e32 v101, v66
	v_sub_f32_e32 v66, v160, v65
	v_exp_f32_e32 v94, v66
	v_sub_f32_e32 v66, v157, v65
	v_exp_f32_e32 v99, v66
	v_sub_f32_e32 v66, v161, v65
	v_exp_f32_e32 v95, v66
	v_sub_f32_e32 v66, v158, v65
	v_exp_f32_e32 v98, v66
	v_sub_f32_e32 v66, v96, v65
	v_exp_f32_e32 v96, v66
	v_sub_f32_e32 v66, v159, v65
	v_sub_f32_e32 v14, v14, v65
	v_sub_f32_e32 v10, v10, v65
	v_exp_f32_e32 v100, v66
	v_sub_f32_e32 v66, v97, v65
	v_exp_f32_e32 v92, v14
	v_exp_f32_e32 v90, v10
	v_sub_f32_e32 v10, v15, v65
	v_sub_f32_e32 v14, v81, v65
	v_exp_f32_e64 v64, -v65
	v_exp_f32_e32 v97, v66
	v_exp_f32_e32 v93, v10
	v_sub_f32_e32 v10, v11, v65
	v_sub_f32_e32 v11, v80, v65
	v_exp_f32_e32 v81, v14
	v_sub_f32_e32 v14, v88, v65
	v_sub_f32_e32 v15, v89, v65
	v_sub_f32_e32 v66, v82, v65
	v_exp_f32_e32 v91, v10
	v_sub_f32_e32 v10, v84, v65
	v_exp_f32_e32 v80, v11
	v_sub_f32_e32 v11, v85, v65
	v_exp_f32_e32 v84, v14
	v_sub_f32_e32 v14, v86, v65
	v_exp_f32_e32 v85, v15
	v_sub_f32_e32 v15, v87, v65
	v_exp_f32_e32 v82, v66
	v_sub_f32_e32 v12, v12, v65
	v_sub_f32_e32 v66, v83, v65
	v_sub_f32_e32 v13, v13, v65
	v_sub_f32_e32 v8, v8, v65
	v_sub_f32_e32 v6, v6, v65
	v_sub_f32_e32 v9, v9, v65
	v_sub_f32_e32 v7, v7, v65
	v_sub_f32_e32 v2, v2, v65
	v_sub_f32_e32 v4, v4, v65
	v_sub_f32_e32 v3, v3, v65
	v_sub_f32_e32 v5, v5, v65
	v_exp_f32_e32 v10, v10
	v_exp_f32_e32 v11, v11
	v_exp_f32_e32 v14, v14
	v_exp_f32_e32 v15, v15
	v_exp_f32_e32 v12, v12
	v_exp_f32_e32 v83, v66
	v_exp_f32_e32 v13, v13
	v_exp_f32_e32 v8, v8
	v_exp_f32_e32 v6, v6
	v_exp_f32_e32 v9, v9
	v_exp_f32_e32 v7, v7
	v_exp_f32_e32 v2, v2
	v_exp_f32_e32 v4, v4
	v_exp_f32_e32 v3, v3
	v_exp_f32_e32 v5, v5
	v_add_f32_e32 v177, v177, v65
	v_pk_mul_f32 v[46:47], v[46:47], v[64:65] op_sel_hi:[1,0]
	v_pk_mul_f32 v[44:45], v[44:45], v[64:65] op_sel_hi:[1,0]
	v_pk_mul_f32 v[42:43], v[42:43], v[64:65] op_sel_hi:[1,0]
	v_pk_mul_f32 v[40:41], v[40:41], v[64:65] op_sel_hi:[1,0]
	v_pk_mul_f32 v[38:39], v[38:39], v[64:65] op_sel_hi:[1,0]
	v_pk_mul_f32 v[36:37], v[36:37], v[64:65] op_sel_hi:[1,0]
	v_pk_mul_f32 v[34:35], v[34:35], v[64:65] op_sel_hi:[1,0]
	v_pk_mul_f32 v[32:33], v[32:33], v[64:65] op_sel_hi:[1,0]
	v_pk_mul_f32 v[30:31], v[30:31], v[64:65] op_sel_hi:[1,0]
	v_pk_mul_f32 v[28:29], v[28:29], v[64:65] op_sel_hi:[1,0]
	v_pk_mul_f32 v[26:27], v[26:27], v[64:65] op_sel_hi:[1,0]
	v_pk_mul_f32 v[24:25], v[24:25], v[64:65] op_sel_hi:[1,0]
	v_pk_mul_f32 v[22:23], v[22:23], v[64:65] op_sel_hi:[1,0]
	v_pk_mul_f32 v[20:21], v[20:21], v[64:65] op_sel_hi:[1,0]
	v_pk_mul_f32 v[18:19], v[18:19], v[64:65] op_sel_hi:[1,0]
	v_pk_mul_f32 v[16:17], v[16:17], v[64:65] op_sel_hi:[1,0]
	v_mul_f32_e32 v173, v173, v64
	v_xor_b32_e32 v64, 0x80000000, v177
	v_mov_b32_e32 v65, v64
	v_mov_b32_e32 v66, v64
	v_mov_b32_e32 v67, v64
	v_mov_b32_e32 v68, v64
	v_mov_b32_e32 v69, v64
	v_mov_b32_e32 v70, v64
	v_mov_b32_e32 v71, v64
	v_mov_b32_e32 v72, v64
	v_mov_b32_e32 v73, v64
	v_mov_b32_e32 v74, v64
	v_mov_b32_e32 v75, v64
	v_mov_b32_e32 v76, v64
	v_mov_b32_e32 v77, v64
	v_mov_b32_e32 v78, v64
	v_mov_b32_e32 v79, v64

; DI float ex2(float x) { return __builtin_amdgcn_exp2f(x); }
; template <int MODE>
; DI void flash_pass(AState& st, const bf16x8* qf, u64 tmask, u64 wmask,
;                    const bf16_t* kbase, size_t kld, const bf16_t* kpe, const bf16_t* vtbase, const float* fbias,
;                    int tq, u64 mysel, bf16_t* smem) {
;     ...
;       int im = (int)0x80000000;
; #pragma unroll
;       for (int r = 0; r < 16; ++r) im = max(im, max(__float_as_int(s0[r]), __float_as_int(s1[r])));
;       im = max(im, __shfl_xor(im, 32));
;       constexpr int TBITS = 0x41800000;
;       f32x16 e0, e1;
; #pragma unroll
;       for (int r = 0; r < 16; ++r) { e0[r] = ex2(s0[r]); e1[r] = ex2(s1[r]); }
;       if (__any(im > TBITS)) {
;         const float d = im > TBITS ? __int_as_float(im) : 0.f;
;         const float a = ex2(-d);
; #pragma unroll
;         for (int r = 0; r < 16; ++r) { e0[r] = ex2(s0[r] - d); e1[r] = ex2(s1[r] - d); st.o[0][r] *= a; st.o[1][r] *= a; }
;         st.l *= a; st.m += d;
; #pragma unroll
;         for (int r = 0; r < 16; ++r) st.mr[r] = -st.m;
;       }
.LBB0_1723:
	v_max3_i32 v90, v157, v161, v156
	v_max3_i32 v91, v160, v158, v96
	v_max3_i32 v90, v90, v159, v97
	v_max3_i32 v91, v91, v14, v10
	v_max3_i32 v90, v90, v15, v11
	v_max3_i32 v91, v91, v84, v80
	v_max3_i32 v90, v90, v85, v81
	v_max3_i32 v91, v91, v88, v86
	v_max3_i32 v90, v90, v89, v87
	v_max3_i32 v91, v91, v82, v12
	v_max3_i32 v90, v90, v83, v13
	v_max3_i32 v91, v91, v8, v6
	v_max3_i32 v90, v90, v9, v7
	v_max3_i32 v91, v91, v2, v4
	v_max3_i32 v90, v90, v3, v5
	v_max_i32_e32 v90, v90, v91
	v_mov_b32_e32 v91, v90
	s_nop 1
	v_permlane32_swap_b32_e32 v91, v90
	v_max_i32_e32 v90, v90, v91
	v_cmp_lt_i32_e32 vcc, s88, v90
	s_cbranch_vccz .LBB0_1725
	s_nop 0
	v_cndmask_b32_e32 v65, 0, v90, vcc
	v_sub_f32_e32 v66, v156, v65
	v_exp_f32_e32 v101, v66
	v_sub_f32_e32 v66, v160, v65
	v_exp_f32_e32 v94, v66
	v_sub_f32_e32 v66, v157, v65
	v_exp_f32_e32 v99, v66
	v_sub_f32_e32 v66, v161, v65
	v_exp_f32_e32 v95, v66
	v_sub_f32_e32 v66, v158, v65
	v_exp_f32_e32 v98, v66
	v_sub_f32_e32 v66, v96, v65
	v_exp_f32_e32 v96, v66
	v_sub_f32_e32 v66, v159, v65
	v_sub_f32_e32 v14, v14, v65
	v_sub_f32_e32 v10, v10, v65
	v_exp_f32_e32 v100, v66
	v_sub_f32_e32 v66, v97, v65
	v_exp_f32_e32 v92, v14
	v_exp_f32_e32 v90, v10
	v_sub_f32_e32 v10, v15, v65
	v_sub_f32_e32 v14, v81, v65
	v_exp_f32_e64 v64, -v65
	v_exp_f32_e32 v97, v66
	v_exp_f32_e32 v93, v10
	v_sub_f32_e32 v10, v11, v65
	v_sub_f32_e32 v11, v80, v65
	v_exp_f32_e32 v81, v14
	v_sub_f32_e32 v14, v88, v65
	v_sub_f32_e32 v15, v89, v65
	v_sub_f32_e32 v66, v82, v65
	v_exp_f32_e32 v91, v10
	v_sub_f32_e32 v10, v84, v65
	v_exp_f32_e32 v80, v11
	v_sub_f32_e32 v11, v85, v65
	v_exp_f32_e32 v84, v14
	v_sub_f32_e32 v14, v86, v65
	v_exp_f32_e32 v85, v15
	v_sub_f32_e32 v15, v87, v65
	v_exp_f32_e32 v82, v66
	v_sub_f32_e32 v12, v12, v65
	v_sub_f32_e32 v66, v83, v65
	v_sub_f32_e32 v13, v13, v65
	v_sub_f32_e32 v8, v8, v65
	v_sub_f32_e32 v6, v6, v65
	v_sub_f32_e32 v9, v9, v65
	v_sub_f32_e32 v7, v7, v65
	v_sub_f32_e32 v2, v2, v65
	v_sub_f32_e32 v4, v4, v65
	v_sub_f32_e32 v3, v3, v65
	v_sub_f32_e32 v5, v5, v65
	v_exp_f32_e32 v10, v10
	v_exp_f32_e32 v11, v11
	v_exp_f32_e32 v14, v14
	v_exp_f32_e32 v15, v15
	v_exp_f32_e32 v12, v12
	v_exp_f32_e32 v83, v66
	v_exp_f32_e32 v13, v13
	v_exp_f32_e32 v8, v8
	v_exp_f32_e32 v6, v6
	v_exp_f32_e32 v9, v9
	v_exp_f32_e32 v7, v7
	v_exp_f32_e32 v2, v2
	v_exp_f32_e32 v4, v4
	v_exp_f32_e32 v3, v3
	v_exp_f32_e32 v5, v5
	v_add_f32_e32 v177, v177, v65
	v_pk_mul_f32 v[46:47], v[46:47], v[64:65] op_sel_hi:[1,0]
	v_pk_mul_f32 v[44:45], v[44:45], v[64:65] op_sel_hi:[1,0]
	v_pk_mul_f32 v[42:43], v[42:43], v[64:65] op_sel_hi:[1,0]
	v_pk_mul_f32 v[40:41], v[40:41], v[64:65] op_sel_hi:[1,0]
	v_pk_mul_f32 v[38:39], v[38:39], v[64:65] op_sel_hi:[1,0]
	v_pk_mul_f32 v[36:37], v[36:37], v[64:65] op_sel_hi:[1,0]
	v_pk_mul_f32 v[34:35], v[34:35], v[64:65] op_sel_hi:[1,0]
	v_pk_mul_f32 v[32:33], v[32:33], v[64:65] op_sel_hi:[1,0]
	v_pk_mul_f32 v[30:31], v[30:31], v[64:65] op_sel_hi:[1,0]
	v_pk_mul_f32 v[28:29], v[28:29], v[64:65] op_sel_hi:[1,0]
	v_pk_mul_f32 v[26:27], v[26:27], v[64:65] op_sel_hi:[1,0]
	v_pk_mul_f32 v[24:25], v[24:25], v[64:65] op_sel_hi:[1,0]
	v_pk_mul_f32 v[22:23], v[22:23], v[64:65] op_sel_hi:[1,0]
	v_pk_mul_f32 v[20:21], v[20:21], v[64:65] op_sel_hi:[1,0]
	v_pk_mul_f32 v[18:19], v[18:19], v[64:65] op_sel_hi:[1,0]
	v_pk_mul_f32 v[16:17], v[16:17], v[64:65] op_sel_hi:[1,0]
	v_mul_f32_e32 v173, v173, v64
	v_xor_b32_e32 v64, 0x80000000, v177
	v_mov_b32_e32 v65, v64
	v_mov_b32_e32 v66, v64
	v_mov_b32_e32 v67, v64
	v_mov_b32_e32 v68, v64
	v_mov_b32_e32 v69, v64
	v_mov_b32_e32 v70, v64
	v_mov_b32_e32 v71, v64
	v_mov_b32_e32 v72, v64
	v_mov_b32_e32 v73, v64
	v_mov_b32_e32 v74, v64
	v_mov_b32_e32 v75, v64
	v_mov_b32_e32 v76, v64
	v_mov_b32_e32 v77, v64
	v_mov_b32_e32 v78, v64
	v_mov_b32_e32 v79, v64
	s_branch .LBB0_1726

; DI float ex2(float x) { return __builtin_amdgcn_exp2f(x); }
; template <int MODE>
; DI void flash_pass(AState& st, const bf16x8* qf, u64 tmask, u64 wmask,
;                    const bf16_t* kbase, size_t kld, const bf16_t* kpe, const bf16_t* vtbase, const float* fbias,
;                    int tq, u64 mysel, bf16_t* smem) {
;     ...
;       int im = (int)0x80000000;
; #pragma unroll
;       for (int r = 0; r < 16; ++r) im = max(im, max(__float_as_int(s0[r]), __float_as_int(s1[r])));
;       im = max(im, __shfl_xor(im, 32));
;       constexpr int TBITS = 0x41800000;
;       f32x16 e0, e1;
; #pragma unroll
;       for (int r = 0; r < 16; ++r) { e0[r] = ex2(s0[r]); e1[r] = ex2(s1[r]); }
;       if (__any(im > TBITS)) {
;         const float d = im > TBITS ? __int_as_float(im) : 0.f;
;         const float a = ex2(-d);
; #pragma unroll
;         for (int r = 0; r < 16; ++r) { e0[r] = ex2(s0[r] - d); e1[r] = ex2(s1[r] - d); st.o[0][r] *= a; st.o[1][r] *= a; }
;         st.l *= a; st.m += d;
; #pragma unroll
;         for (int r = 0; r < 16; ++r) st.mr[r] = -st.m;
;       }
.LBB0_1791:
	s_nop 10
	v_max3_i32 v2, v65, v81, v64
	v_max3_i32 v3, v80, v66, v82
	v_max3_i32 v2, v2, v67, v83
	v_max3_i32 v3, v3, v68, v84
	v_max3_i32 v2, v2, v69, v85
	v_max3_i32 v3, v3, v70, v86
	v_max3_i32 v2, v2, v71, v87
	v_max3_i32 v3, v3, v72, v88
	v_max3_i32 v2, v2, v73, v89
	v_max3_i32 v3, v3, v74, v90
	v_max3_i32 v2, v2, v75, v91
	v_max3_i32 v3, v3, v76, v92
	v_max3_i32 v2, v2, v77, v93
	v_max3_i32 v3, v3, v78, v94
	v_max3_i32 v2, v2, v79, v95
	v_max_i32_e32 v2, v2, v3
	v_mov_b32_e32 v3, v2
	s_nop 1
	v_permlane32_swap_b32_e32 v3, v2
	v_max_i32_e32 v2, v2, v3
	v_cmp_lt_i32_e32 vcc, s88, v2
	s_cbranch_vccz .LBB0_1793
	s_nop 0
	v_cndmask_b32_e32 v49, 0, v2, vcc
	v_sub_f32_e32 v2, v64, v49
	v_exp_f32_e32 v181, v2
	v_sub_f32_e32 v2, v80, v49
	v_exp_f32_e32 v80, v2
	v_sub_f32_e32 v2, v65, v49
	v_exp_f32_e32 v179, v2
	v_sub_f32_e32 v2, v81, v49
	v_exp_f32_e32 v81, v2
	v_sub_f32_e32 v2, v66, v49
	v_exp_f32_e32 v178, v2
	v_sub_f32_e32 v2, v82, v49
	v_exp_f32_e32 v82, v2
	v_sub_f32_e32 v2, v67, v49
	v_exp_f32_e32 v180, v2
	v_sub_f32_e32 v2, v83, v49
	v_sub_f32_e32 v50, v76, v49
	v_exp_f32_e32 v83, v2
	v_sub_f32_e32 v2, v68, v49
	v_exp_f32_e32 v64, v50
	v_sub_f32_e32 v50, v92, v49
	v_exp_f32_e32 v68, v2
	v_sub_f32_e32 v2, v84, v49
	v_exp_f32_e32 v66, v50
	v_sub_f32_e32 v50, v77, v49
	v_exp_f32_e32 v8, v2
	v_sub_f32_e32 v2, v69, v49
	v_exp_f32_e32 v65, v50
	v_sub_f32_e32 v50, v93, v49
	v_exp_f32_e32 v69, v2
	v_sub_f32_e32 v2, v85, v49
	v_exp_f32_e32 v67, v50
	v_sub_f32_e32 v50, v78, v49
	v_exp_f32_e32 v9, v2
	v_sub_f32_e32 v2, v70, v49
	v_sub_f32_e32 v4, v87, v49
	v_exp_f32_e32 v70, v50
	v_sub_f32_e32 v50, v94, v49
	v_exp_f32_e64 v48, -v49
	v_sub_f32_e32 v3, v86, v49
	v_exp_f32_e32 v7, v4
	v_sub_f32_e32 v4, v72, v49
	v_sub_f32_e32 v5, v73, v49
	v_sub_f32_e32 v12, v74, v49
	v_sub_f32_e32 v13, v75, v49
	v_exp_f32_e32 v72, v50
	v_sub_f32_e32 v50, v79, v49
	v_exp_f32_e32 v6, v3
	v_sub_f32_e32 v3, v71, v49
	v_exp_f32_e32 v10, v4
	v_sub_f32_e32 v4, v88, v49
	v_exp_f32_e32 v11, v5
	v_sub_f32_e32 v5, v89, v49
	v_exp_f32_e32 v14, v12
	v_sub_f32_e32 v12, v90, v49
	v_exp_f32_e32 v15, v13
	v_sub_f32_e32 v13, v91, v49
	v_exp_f32_e32 v71, v50
	v_sub_f32_e32 v50, v95, v49
	v_exp_f32_e32 v2, v2
	v_exp_f32_e32 v3, v3
	v_exp_f32_e32 v4, v4
	v_exp_f32_e32 v5, v5
	v_exp_f32_e32 v12, v12
	v_exp_f32_e32 v13, v13
	v_exp_f32_e32 v73, v50
	v_add_f32_e32 v0, v0, v49
	v_pk_mul_f32 v[46:47], v[46:47], v[48:49] op_sel_hi:[1,0]
	v_pk_mul_f32 v[44:45], v[44:45], v[48:49] op_sel_hi:[1,0]
	v_pk_mul_f32 v[42:43], v[42:43], v[48:49] op_sel_hi:[1,0]
	v_pk_mul_f32 v[40:41], v[40:41], v[48:49] op_sel_hi:[1,0]
	v_pk_mul_f32 v[38:39], v[38:39], v[48:49] op_sel_hi:[1,0]
	v_pk_mul_f32 v[36:37], v[36:37], v[48:49] op_sel_hi:[1,0]
	v_pk_mul_f32 v[34:35], v[34:35], v[48:49] op_sel_hi:[1,0]
	v_pk_mul_f32 v[32:33], v[32:33], v[48:49] op_sel_hi:[1,0]
	v_pk_mul_f32 v[30:31], v[30:31], v[48:49] op_sel_hi:[1,0]
	v_pk_mul_f32 v[28:29], v[28:29], v[48:49] op_sel_hi:[1,0]
	v_pk_mul_f32 v[26:27], v[26:27], v[48:49] op_sel_hi:[1,0]
	v_pk_mul_f32 v[24:25], v[24:25], v[48:49] op_sel_hi:[1,0]
	v_pk_mul_f32 v[22:23], v[22:23], v[48:49] op_sel_hi:[1,0]
	v_pk_mul_f32 v[20:21], v[20:21], v[48:49] op_sel_hi:[1,0]
	v_pk_mul_f32 v[18:19], v[18:19], v[48:49] op_sel_hi:[1,0]
	v_pk_mul_f32 v[16:17], v[16:17], v[48:49] op_sel_hi:[1,0]
	v_mul_f32_e32 v171, v171, v48
	v_xor_b32_e32 v48, 0x80000000, v0
	v_mov_b32_e32 v49, v48
	v_mov_b32_e32 v50, v48
	v_mov_b32_e32 v51, v48
	v_mov_b32_e32 v52, v48
	v_mov_b32_e32 v53, v48
	v_mov_b32_e32 v54, v48
	v_mov_b32_e32 v55, v48
	v_mov_b32_e32 v56, v48
	v_mov_b32_e32 v57, v48
	v_mov_b32_e32 v58, v48
	v_mov_b32_e32 v59, v48
	v_mov_b32_e32 v60, v48
	v_mov_b32_e32 v61, v48
	v_mov_b32_e32 v62, v48
	v_mov_b32_e32 v63, v48
	s_branch .LBB0_1794

; DI float ex2(float x) { return __builtin_amdgcn_exp2f(x); }
; template <int MODE>
; DI void flash_pass(AState& st, const bf16x8* qf, u64 tmask, u64 wmask,
;                    const bf16_t* kbase, size_t kld, const bf16_t* kpe, const bf16_t* vtbase, const float* fbias,
;                    int tq, u64 mysel, bf16_t* smem) {
;     ...
;       int im = (int)0x80000000;
; #pragma unroll
;       for (int r = 0; r < 16; ++r) im = max(im, max(__float_as_int(s0[r]), __float_as_int(s1[r])));
;       im = max(im, __shfl_xor(im, 32));
;       constexpr int TBITS = 0x41800000;
;       f32x16 e0, e1;
; #pragma unroll
;       for (int r = 0; r < 16; ++r) { e0[r] = ex2(s0[r]); e1[r] = ex2(s1[r]); }
;       if (__any(im > TBITS)) {
;         const float d = im > TBITS ? __int_as_float(im) : 0.f;
;         const float a = ex2(-d);
; #pragma unroll
;         for (int r = 0; r < 16; ++r) { e0[r] = ex2(s0[r] - d); e1[r] = ex2(s1[r] - d); st.o[0][r] *= a; st.o[1][r] *= a; }
;         st.l *= a; st.m += d;
; #pragma unroll
;         for (int r = 0; r < 16; ++r) st.mr[r] = -st.m;
;       }
.LBB0_1803:
	s_nop 10
	v_max3_i32 v2, v65, v81, v64
	v_max3_i32 v3, v80, v66, v82
	v_max3_i32 v2, v2, v67, v83
	v_max3_i32 v3, v3, v68, v84
	v_max3_i32 v2, v2, v69, v85
	v_max3_i32 v3, v3, v70, v86
	v_max3_i32 v2, v2, v71, v87
	v_max3_i32 v3, v3, v72, v88
	v_max3_i32 v2, v2, v73, v89
	v_max3_i32 v3, v3, v74, v90
	v_max3_i32 v2, v2, v75, v91
	v_max3_i32 v3, v3, v76, v92
	v_max3_i32 v2, v2, v77, v93
	v_max3_i32 v3, v3, v78, v94
	v_max3_i32 v2, v2, v79, v95
	v_max_i32_e32 v2, v2, v3
	v_mov_b32_e32 v3, v2
	s_nop 1
	v_permlane32_swap_b32_e32 v3, v2
	v_max_i32_e32 v2, v2, v3
	v_cmp_lt_i32_e32 vcc, s88, v2
	s_cbranch_vccz .LBB0_1805
	s_nop 0
	v_cndmask_b32_e32 v49, 0, v2, vcc
	v_sub_f32_e32 v2, v64, v49
	v_exp_f32_e32 v180, v2
	v_sub_f32_e32 v2, v80, v49
	v_exp_f32_e32 v80, v2
	v_sub_f32_e32 v2, v65, v49
	v_exp_f32_e32 v178, v2
	v_sub_f32_e32 v2, v81, v49
	v_exp_f32_e32 v81, v2
	v_sub_f32_e32 v2, v66, v49
	v_exp_f32_e32 v177, v2
	v_sub_f32_e32 v2, v82, v49
	v_exp_f32_e32 v82, v2
	v_sub_f32_e32 v2, v67, v49
	v_exp_f32_e32 v179, v2
	v_sub_f32_e32 v2, v83, v49
	v_sub_f32_e32 v50, v76, v49
	v_exp_f32_e32 v83, v2
	v_sub_f32_e32 v2, v68, v49
	v_exp_f32_e32 v64, v50
	v_sub_f32_e32 v50, v92, v49
	v_exp_f32_e32 v68, v2
	v_sub_f32_e32 v2, v84, v49
	v_exp_f32_e32 v66, v50
	v_sub_f32_e32 v50, v77, v49
	v_exp_f32_e32 v8, v2
	v_sub_f32_e32 v2, v69, v49
	v_exp_f32_e32 v65, v50
	v_sub_f32_e32 v50, v93, v49
	v_exp_f32_e32 v69, v2
	v_sub_f32_e32 v2, v85, v49
	v_exp_f32_e32 v67, v50
	v_sub_f32_e32 v50, v78, v49
	v_exp_f32_e32 v9, v2
	v_sub_f32_e32 v2, v70, v49
	v_sub_f32_e32 v4, v87, v49
	v_exp_f32_e32 v70, v50
	v_sub_f32_e32 v50, v94, v49
	v_exp_f32_e64 v48, -v49
	v_sub_f32_e32 v3, v86, v49
	v_exp_f32_e32 v7, v4
	v_sub_f32_e32 v4, v72, v49
	v_sub_f32_e32 v5, v73, v49
	v_sub_f32_e32 v12, v74, v49
	v_sub_f32_e32 v13, v75, v49
	v_exp_f32_e32 v72, v50
	v_sub_f32_e32 v50, v79, v49
	v_exp_f32_e32 v6, v3
	v_sub_f32_e32 v3, v71, v49
	v_exp_f32_e32 v10, v4
	v_sub_f32_e32 v4, v88, v49
	v_exp_f32_e32 v11, v5
	v_sub_f32_e32 v5, v89, v49
	v_exp_f32_e32 v14, v12
	v_sub_f32_e32 v12, v90, v49
	v_exp_f32_e32 v15, v13
	v_sub_f32_e32 v13, v91, v49
	v_exp_f32_e32 v71, v50
	v_sub_f32_e32 v50, v95, v49
	v_exp_f32_e32 v2, v2
	v_exp_f32_e32 v3, v3
	v_exp_f32_e32 v4, v4
	v_exp_f32_e32 v5, v5
	v_exp_f32_e32 v12, v12
	v_exp_f32_e32 v13, v13
	v_exp_f32_e32 v73, v50
	v_add_f32_e32 v0, v0, v49
	v_pk_mul_f32 v[46:47], v[46:47], v[48:49] op_sel_hi:[1,0]
	v_pk_mul_f32 v[44:45], v[44:45], v[48:49] op_sel_hi:[1,0]
	v_pk_mul_f32 v[42:43], v[42:43], v[48:49] op_sel_hi:[1,0]
	v_pk_mul_f32 v[40:41], v[40:41], v[48:49] op_sel_hi:[1,0]
	v_pk_mul_f32 v[38:39], v[38:39], v[48:49] op_sel_hi:[1,0]
	v_pk_mul_f32 v[36:37], v[36:37], v[48:49] op_sel_hi:[1,0]
	v_pk_mul_f32 v[34:35], v[34:35], v[48:49] op_sel_hi:[1,0]
	v_pk_mul_f32 v[32:33], v[32:33], v[48:49] op_sel_hi:[1,0]
	v_pk_mul_f32 v[30:31], v[30:31], v[48:49] op_sel_hi:[1,0]
	v_pk_mul_f32 v[28:29], v[28:29], v[48:49] op_sel_hi:[1,0]
	v_pk_mul_f32 v[26:27], v[26:27], v[48:49] op_sel_hi:[1,0]
	v_pk_mul_f32 v[24:25], v[24:25], v[48:49] op_sel_hi:[1,0]
	v_pk_mul_f32 v[22:23], v[22:23], v[48:49] op_sel_hi:[1,0]
	v_pk_mul_f32 v[20:21], v[20:21], v[48:49] op_sel_hi:[1,0]
	v_pk_mul_f32 v[18:19], v[18:19], v[48:49] op_sel_hi:[1,0]
	v_pk_mul_f32 v[16:17], v[16:17], v[48:49] op_sel_hi:[1,0]
	v_mul_f32_e32 v171, v171, v48
	v_xor_b32_e32 v48, 0x80000000, v0
	v_mov_b32_e32 v49, v48
	v_mov_b32_e32 v50, v48
	v_mov_b32_e32 v51, v48
	v_mov_b32_e32 v52, v48
	v_mov_b32_e32 v53, v48
	v_mov_b32_e32 v54, v48
	v_mov_b32_e32 v55, v48
	v_mov_b32_e32 v56, v48
	v_mov_b32_e32 v57, v48
	v_mov_b32_e32 v58, v48
	v_mov_b32_e32 v59, v48
	v_mov_b32_e32 v60, v48
	v_mov_b32_e32 v61, v48
	v_mov_b32_e32 v62, v48
	v_mov_b32_e32 v63, v48
	s_branch .LBB0_1806
